# P4/P6' epilogues de-serialised (g_fin loads ahead of the panel rendezvous) + XCD-local seams P4->P5->P6' with 3us/XCD start stagger (spin cap as the baseline's barriers)
# speedup vs baseline: 1.0031x; 1.0031x over previous
.Lxl_b4_spin:
	s_sleep 1
	global_load_dword v5, v3, s[6:7] sc1
	s_waitcnt vmcnt(0)
	v_readfirstlane_b32 s9, v5
	s_cmp_lg_u32 s9, 3
	s_cbranch_scc1 .Lxl_b4_acq
	s_add_i32 s11, s11, 1
	s_cmp_lt_u32 s11, 1048576
	s_cbranch_scc1 .Lxl_b4_spin

.Lxl_b5_spin:
	s_sleep 1
	global_load_dword v5, v3, s[6:7] sc1
	s_waitcnt vmcnt(0)
	v_readfirstlane_b32 s9, v5
	s_cmp_lg_u32 s9, 4
	s_cbranch_scc1 .Lxl_b5_acq
	s_add_i32 s11, s11, 1
	s_cmp_lt_u32 s11, 1048576
	s_cbranch_scc1 .Lxl_b5_spin

.LBB0_677:
	s_lshl_b32 s3, s2, 8
	s_add_i32 s3, s3, s77
	v_add_u32_e32 v181, s3, v172
	v_lshl_add_u32 v185, v173, 3, s44
	v_lshlrev_b32_e32 v253, 2, v181
	v_lshlrev_b32_e32 v252, 2, v185
	v_lshlrev_b32_e32 v187, 12, v181
	v_lshl_add_u32 v187, v185, 1, v187
	v_lshlrev_b32_e32 v181, 13, v181
	v_lshl_add_u32 v185, v185, 2, v181
	global_load_dword v164, v253, s[12:13]
	global_load_dword v165, v253, s[12:13] offset:64
	global_load_dword v166, v253, s[12:13] offset:128
	global_load_dword v167, v253, s[12:13] offset:192
	global_load_dword v168, v253, s[12:13] offset:512
	global_load_dword v169, v253, s[12:13] offset:576
	global_load_dword v170, v253, s[12:13] offset:640
	global_load_dword v171, v253, s[12:13] offset:704
	global_load_dwordx4 v[148:151], v252, s[14:15] offset:0
	global_load_dwordx4 v[152:155], v252, s[14:15] offset:16
	global_load_dwordx4 v[156:159], v252, s[14:15] offset:512
	global_load_dwordx4 v[160:163], v252, s[14:15] offset:528
	s_mov_b32 s98, s18
	s_mov_b32 s99, s19
	s_nop 0
	global_load_dwordx4 v[188:191], v187, s[98:99]
	global_load_dwordx4 v[192:195], v187, s[98:99] offset:256
	s_add_u32 s98, s18, 0x10000
	s_addc_u32 s99, s19, 0
	s_nop 0
	global_load_dwordx4 v[196:199], v187, s[98:99]
	global_load_dwordx4 v[200:203], v187, s[98:99] offset:256
	s_add_u32 s98, s18, 0x20000
	s_addc_u32 s99, s19, 0
	s_nop 0
	global_load_dwordx4 v[204:207], v187, s[98:99]
	global_load_dwordx4 v[208:211], v187, s[98:99] offset:256
	s_add_u32 s98, s18, 0x30000
	s_addc_u32 s99, s19, 0
	s_nop 0
	global_load_dwordx4 v[212:215], v187, s[98:99]
	global_load_dwordx4 v[216:219], v187, s[98:99] offset:256
	s_add_u32 s98, s18, 0x80000
	s_addc_u32 s99, s19, 0
	s_nop 0
	global_load_dwordx4 v[220:223], v187, s[98:99]
	global_load_dwordx4 v[224:227], v187, s[98:99] offset:256
	s_add_u32 s98, s18, 0x90000
	s_addc_u32 s99, s19, 0
	s_nop 0
	global_load_dwordx4 v[228:231], v187, s[98:99]
	global_load_dwordx4 v[232:235], v187, s[98:99] offset:256
	s_add_u32 s98, s18, 0xa0000
	s_addc_u32 s99, s19, 0
	s_nop 0
	global_load_dwordx4 v[236:239], v187, s[98:99]
	global_load_dwordx4 v[240:243], v187, s[98:99] offset:256
	s_add_u32 s98, s18, 0xb0000
	s_addc_u32 s99, s19, 0
	s_nop 0
	global_load_dwordx4 v[244:247], v187, s[98:99]
	global_load_dwordx4 v[248:251], v187, s[98:99] offset:256
	s_waitcnt vmcnt(15)
	v_fmamk_f32 v184, v164, 0x3a000000, v177
	v_rcp_f32_e32 v184, v184
	v_and_b32_e32 v129, 0xffff0000, v188
	v_lshlrev_b32_e32 v128, 16, v188
	v_and_b32_e32 v131, 0xffff0000, v189
	v_lshlrev_b32_e32 v130, 16, v189
	v_and_b32_e32 v133, 0xffff0000, v190
	v_lshlrev_b32_e32 v132, 16, v190
	v_and_b32_e32 v135, 0xffff0000, v191
	v_lshlrev_b32_e32 v134, 16, v191
	v_pk_mul_f32 v[128:129], v[148:149], v[128:129]
	v_pk_mul_f32 v[130:131], v[150:151], v[130:131]
	v_pk_mul_f32 v[132:133], v[152:153], v[132:133]
	v_pk_mul_f32 v[134:135], v[154:155], v[134:135]
	v_pk_fma_f32 v[124:125], v[124:125], v[184:185], v[128:129] op_sel_hi:[1,0,1]
	v_pk_fma_f32 v[126:127], v[126:127], v[184:185], v[130:131] op_sel_hi:[1,0,1]
	v_pk_fma_f32 v[120:121], v[120:121], v[184:185], v[132:133] op_sel_hi:[1,0,1]
	v_pk_fma_f32 v[122:123], v[122:123], v[184:185], v[134:135] op_sel_hi:[1,0,1]
	v_pk_mul_f32 v[182:183], v[124:125], v[124:125]
	v_pk_fma_f32 v[182:183], v[126:127], v[126:127], v[182:183]
	v_pk_fma_f32 v[182:183], v[120:121], v[120:121], v[182:183]
	v_pk_fma_f32 v[182:183], v[122:123], v[122:123], v[182:183]
	s_waitcnt vmcnt(14)
	v_and_b32_e32 v129, 0xffff0000, v192
	v_lshlrev_b32_e32 v128, 16, v192
	v_and_b32_e32 v131, 0xffff0000, v193
	v_lshlrev_b32_e32 v130, 16, v193
	v_and_b32_e32 v133, 0xffff0000, v194
	v_lshlrev_b32_e32 v132, 16, v194
	v_and_b32_e32 v135, 0xffff0000, v195
	v_lshlrev_b32_e32 v134, 16, v195
	v_pk_mul_f32 v[128:129], v[156:157], v[128:129]
	v_pk_mul_f32 v[130:131], v[158:159], v[130:131]
	v_pk_mul_f32 v[132:133], v[160:161], v[132:133]
	v_pk_mul_f32 v[134:135], v[162:163], v[134:135]
	v_pk_fma_f32 v[116:117], v[116:117], v[184:185], v[128:129] op_sel_hi:[1,0,1]
	v_pk_fma_f32 v[118:119], v[118:119], v[184:185], v[130:131] op_sel_hi:[1,0,1]
	v_pk_fma_f32 v[112:113], v[112:113], v[184:185], v[132:133] op_sel_hi:[1,0,1]
	v_pk_fma_f32 v[114:115], v[114:115], v[184:185], v[134:135] op_sel_hi:[1,0,1]
	v_pk_fma_f32 v[182:183], v[116:117], v[116:117], v[182:183]
	v_pk_fma_f32 v[182:183], v[118:119], v[118:119], v[182:183]
	v_pk_fma_f32 v[182:183], v[112:113], v[112:113], v[182:183]
	v_pk_fma_f32 v[182:183], v[114:115], v[114:115], v[182:183]
	v_add_f32_e32 v164, v182, v183
	s_waitcnt vmcnt(13)
	v_fmamk_f32 v184, v165, 0x3a000000, v177
	v_rcp_f32_e32 v184, v184
	v_and_b32_e32 v129, 0xffff0000, v196
	v_lshlrev_b32_e32 v128, 16, v196
	v_and_b32_e32 v131, 0xffff0000, v197
	v_lshlrev_b32_e32 v130, 16, v197
	v_and_b32_e32 v133, 0xffff0000, v198
	v_lshlrev_b32_e32 v132, 16, v198
	v_and_b32_e32 v135, 0xffff0000, v199
	v_lshlrev_b32_e32 v134, 16, v199
	v_pk_mul_f32 v[128:129], v[148:149], v[128:129]
	v_pk_mul_f32 v[130:131], v[150:151], v[130:131]
	v_pk_mul_f32 v[132:133], v[152:153], v[132:133]
	v_pk_mul_f32 v[134:135], v[154:155], v[134:135]
	v_pk_fma_f32 v[108:109], v[108:109], v[184:185], v[128:129] op_sel_hi:[1,0,1]
	v_pk_fma_f32 v[110:111], v[110:111], v[184:185], v[130:131] op_sel_hi:[1,0,1]
	v_pk_fma_f32 v[104:105], v[104:105], v[184:185], v[132:133] op_sel_hi:[1,0,1]
	v_pk_fma_f32 v[106:107], v[106:107], v[184:185], v[134:135] op_sel_hi:[1,0,1]
	v_pk_mul_f32 v[182:183], v[108:109], v[108:109]
	v_pk_fma_f32 v[182:183], v[110:111], v[110:111], v[182:183]
	v_pk_fma_f32 v[182:183], v[104:105], v[104:105], v[182:183]
	v_pk_fma_f32 v[182:183], v[106:107], v[106:107], v[182:183]
	s_waitcnt vmcnt(12)
	v_and_b32_e32 v129, 0xffff0000, v200
	v_lshlrev_b32_e32 v128, 16, v200
	v_and_b32_e32 v131, 0xffff0000, v201
	v_lshlrev_b32_e32 v130, 16, v201
	v_and_b32_e32 v133, 0xffff0000, v202
	v_lshlrev_b32_e32 v132, 16, v202
	v_and_b32_e32 v135, 0xffff0000, v203
	v_lshlrev_b32_e32 v134, 16, v203
	v_pk_mul_f32 v[128:129], v[156:157], v[128:129]
	v_pk_mul_f32 v[130:131], v[158:159], v[130:131]
	v_pk_mul_f32 v[132:133], v[160:161], v[132:133]
	v_pk_mul_f32 v[134:135], v[162:163], v[134:135]
	v_pk_fma_f32 v[100:101], v[100:101], v[184:185], v[128:129] op_sel_hi:[1,0,1]
	v_pk_fma_f32 v[102:103], v[102:103], v[184:185], v[130:131] op_sel_hi:[1,0,1]
	v_pk_fma_f32 v[96:97], v[96:97], v[184:185], v[132:133] op_sel_hi:[1,0,1]
	v_pk_fma_f32 v[98:99], v[98:99], v[184:185], v[134:135] op_sel_hi:[1,0,1]
	v_pk_fma_f32 v[182:183], v[100:101], v[100:101], v[182:183]
	v_pk_fma_f32 v[182:183], v[102:103], v[102:103], v[182:183]
	v_pk_fma_f32 v[182:183], v[96:97], v[96:97], v[182:183]
	v_pk_fma_f32 v[182:183], v[98:99], v[98:99], v[182:183]
	v_add_f32_e32 v165, v182, v183
	s_waitcnt vmcnt(11)
	v_fmamk_f32 v184, v166, 0x3a000000, v177
	v_rcp_f32_e32 v184, v184
	v_and_b32_e32 v129, 0xffff0000, v204
	v_lshlrev_b32_e32 v128, 16, v204
	v_and_b32_e32 v131, 0xffff0000, v205
	v_lshlrev_b32_e32 v130, 16, v205
	v_and_b32_e32 v133, 0xffff0000, v206
	v_lshlrev_b32_e32 v132, 16, v206
	v_and_b32_e32 v135, 0xffff0000, v207
	v_lshlrev_b32_e32 v134, 16, v207
	v_pk_mul_f32 v[128:129], v[148:149], v[128:129]
	v_pk_mul_f32 v[130:131], v[150:151], v[130:131]
	v_pk_mul_f32 v[132:133], v[152:153], v[132:133]
	v_pk_mul_f32 v[134:135], v[154:155], v[134:135]
	v_pk_fma_f32 v[92:93], v[92:93], v[184:185], v[128:129] op_sel_hi:[1,0,1]
	v_pk_fma_f32 v[94:95], v[94:95], v[184:185], v[130:131] op_sel_hi:[1,0,1]
	v_pk_fma_f32 v[88:89], v[88:89], v[184:185], v[132:133] op_sel_hi:[1,0,1]
	v_pk_fma_f32 v[90:91], v[90:91], v[184:185], v[134:135] op_sel_hi:[1,0,1]
	v_pk_mul_f32 v[182:183], v[92:93], v[92:93]
	v_pk_fma_f32 v[182:183], v[94:95], v[94:95], v[182:183]
	v_pk_fma_f32 v[182:183], v[88:89], v[88:89], v[182:183]
	v_pk_fma_f32 v[182:183], v[90:91], v[90:91], v[182:183]
	s_waitcnt vmcnt(10)
	v_and_b32_e32 v129, 0xffff0000, v208
	v_lshlrev_b32_e32 v128, 16, v208
	v_and_b32_e32 v131, 0xffff0000, v209
	v_lshlrev_b32_e32 v130, 16, v209
	v_and_b32_e32 v133, 0xffff0000, v210
	v_lshlrev_b32_e32 v132, 16, v210
	v_and_b32_e32 v135, 0xffff0000, v211
	v_lshlrev_b32_e32 v134, 16, v211
	v_pk_mul_f32 v[128:129], v[156:157], v[128:129]
	v_pk_mul_f32 v[130:131], v[158:159], v[130:131]
	v_pk_mul_f32 v[132:133], v[160:161], v[132:133]
	v_pk_mul_f32 v[134:135], v[162:163], v[134:135]
	v_pk_fma_f32 v[84:85], v[84:85], v[184:185], v[128:129] op_sel_hi:[1,0,1]
	v_pk_fma_f32 v[86:87], v[86:87], v[184:185], v[130:131] op_sel_hi:[1,0,1]
	v_pk_fma_f32 v[80:81], v[80:81], v[184:185], v[132:133] op_sel_hi:[1,0,1]
	v_pk_fma_f32 v[82:83], v[82:83], v[184:185], v[134:135] op_sel_hi:[1,0,1]
	v_pk_fma_f32 v[182:183], v[84:85], v[84:85], v[182:183]
	v_pk_fma_f32 v[182:183], v[86:87], v[86:87], v[182:183]
	v_pk_fma_f32 v[182:183], v[80:81], v[80:81], v[182:183]
	v_pk_fma_f32 v[182:183], v[82:83], v[82:83], v[182:183]
	v_add_f32_e32 v166, v182, v183
	s_waitcnt vmcnt(9)
	v_fmamk_f32 v184, v167, 0x3a000000, v177
	v_rcp_f32_e32 v184, v184
	v_and_b32_e32 v129, 0xffff0000, v212
	v_lshlrev_b32_e32 v128, 16, v212
	v_and_b32_e32 v131, 0xffff0000, v213
	v_lshlrev_b32_e32 v130, 16, v213
	v_and_b32_e32 v133, 0xffff0000, v214
	v_lshlrev_b32_e32 v132, 16, v214
	v_and_b32_e32 v135, 0xffff0000, v215
	v_lshlrev_b32_e32 v134, 16, v215
	v_pk_mul_f32 v[128:129], v[148:149], v[128:129]
	v_pk_mul_f32 v[130:131], v[150:151], v[130:131]
	v_pk_mul_f32 v[132:133], v[152:153], v[132:133]
	v_pk_mul_f32 v[134:135], v[154:155], v[134:135]
	v_pk_fma_f32 v[76:77], v[76:77], v[184:185], v[128:129] op_sel_hi:[1,0,1]
	v_pk_fma_f32 v[78:79], v[78:79], v[184:185], v[130:131] op_sel_hi:[1,0,1]
	v_pk_fma_f32 v[72:73], v[72:73], v[184:185], v[132:133] op_sel_hi:[1,0,1]
	v_pk_fma_f32 v[74:75], v[74:75], v[184:185], v[134:135] op_sel_hi:[1,0,1]
	v_pk_mul_f32 v[182:183], v[76:77], v[76:77]
	v_pk_fma_f32 v[182:183], v[78:79], v[78:79], v[182:183]
	v_pk_fma_f32 v[182:183], v[72:73], v[72:73], v[182:183]
	v_pk_fma_f32 v[182:183], v[74:75], v[74:75], v[182:183]
	s_waitcnt vmcnt(8)
	v_and_b32_e32 v129, 0xffff0000, v216
	v_lshlrev_b32_e32 v128, 16, v216
	v_and_b32_e32 v131, 0xffff0000, v217
	v_lshlrev_b32_e32 v130, 16, v217
	v_and_b32_e32 v133, 0xffff0000, v218
	v_lshlrev_b32_e32 v132, 16, v218
	v_and_b32_e32 v135, 0xffff0000, v219
	v_lshlrev_b32_e32 v134, 16, v219
	v_pk_mul_f32 v[128:129], v[156:157], v[128:129]
	v_pk_mul_f32 v[130:131], v[158:159], v[130:131]
	v_pk_mul_f32 v[132:133], v[160:161], v[132:133]
	v_pk_mul_f32 v[134:135], v[162:163], v[134:135]
	v_pk_fma_f32 v[68:69], v[68:69], v[184:185], v[128:129] op_sel_hi:[1,0,1]
	v_pk_fma_f32 v[70:71], v[70:71], v[184:185], v[130:131] op_sel_hi:[1,0,1]
	v_pk_fma_f32 v[64:65], v[64:65], v[184:185], v[132:133] op_sel_hi:[1,0,1]
	v_pk_fma_f32 v[66:67], v[66:67], v[184:185], v[134:135] op_sel_hi:[1,0,1]
	v_pk_fma_f32 v[182:183], v[68:69], v[68:69], v[182:183]
	v_pk_fma_f32 v[182:183], v[70:71], v[70:71], v[182:183]
	v_pk_fma_f32 v[182:183], v[64:65], v[64:65], v[182:183]
	v_pk_fma_f32 v[182:183], v[66:67], v[66:67], v[182:183]
	v_add_f32_e32 v167, v182, v183
	s_waitcnt vmcnt(7)
	v_fmamk_f32 v184, v168, 0x3a000000, v177
	v_rcp_f32_e32 v184, v184
	v_and_b32_e32 v129, 0xffff0000, v220
	v_lshlrev_b32_e32 v128, 16, v220
	v_and_b32_e32 v131, 0xffff0000, v221
	v_lshlrev_b32_e32 v130, 16, v221
	v_and_b32_e32 v133, 0xffff0000, v222
	v_lshlrev_b32_e32 v132, 16, v222
	v_and_b32_e32 v135, 0xffff0000, v223
	v_lshlrev_b32_e32 v134, 16, v223
	v_pk_mul_f32 v[128:129], v[148:149], v[128:129]
	v_pk_mul_f32 v[130:131], v[150:151], v[130:131]
	v_pk_mul_f32 v[132:133], v[152:153], v[132:133]
	v_pk_mul_f32 v[134:135], v[154:155], v[134:135]
	v_pk_fma_f32 v[60:61], v[60:61], v[184:185], v[128:129] op_sel_hi:[1,0,1]
	v_pk_fma_f32 v[62:63], v[62:63], v[184:185], v[130:131] op_sel_hi:[1,0,1]
	v_pk_fma_f32 v[56:57], v[56:57], v[184:185], v[132:133] op_sel_hi:[1,0,1]
	v_pk_fma_f32 v[58:59], v[58:59], v[184:185], v[134:135] op_sel_hi:[1,0,1]
	v_pk_mul_f32 v[182:183], v[60:61], v[60:61]
	v_pk_fma_f32 v[182:183], v[62:63], v[62:63], v[182:183]
	v_pk_fma_f32 v[182:183], v[56:57], v[56:57], v[182:183]
	v_pk_fma_f32 v[182:183], v[58:59], v[58:59], v[182:183]
	s_waitcnt vmcnt(6)
	v_and_b32_e32 v129, 0xffff0000, v224
	v_lshlrev_b32_e32 v128, 16, v224
	v_and_b32_e32 v131, 0xffff0000, v225
	v_lshlrev_b32_e32 v130, 16, v225
	v_and_b32_e32 v133, 0xffff0000, v226
	v_lshlrev_b32_e32 v132, 16, v226
	v_and_b32_e32 v135, 0xffff0000, v227
	v_lshlrev_b32_e32 v134, 16, v227
	v_pk_mul_f32 v[128:129], v[156:157], v[128:129]
	v_pk_mul_f32 v[130:131], v[158:159], v[130:131]
	v_pk_mul_f32 v[132:133], v[160:161], v[132:133]
	v_pk_mul_f32 v[134:135], v[162:163], v[134:135]
	v_pk_fma_f32 v[52:53], v[52:53], v[184:185], v[128:129] op_sel_hi:[1,0,1]
	v_pk_fma_f32 v[54:55], v[54:55], v[184:185], v[130:131] op_sel_hi:[1,0,1]
	v_pk_fma_f32 v[48:49], v[48:49], v[184:185], v[132:133] op_sel_hi:[1,0,1]
	v_pk_fma_f32 v[50:51], v[50:51], v[184:185], v[134:135] op_sel_hi:[1,0,1]
	v_pk_fma_f32 v[182:183], v[52:53], v[52:53], v[182:183]
	v_pk_fma_f32 v[182:183], v[54:55], v[54:55], v[182:183]
	v_pk_fma_f32 v[182:183], v[48:49], v[48:49], v[182:183]
	v_pk_fma_f32 v[182:183], v[50:51], v[50:51], v[182:183]
	v_add_f32_e32 v168, v182, v183
	s_waitcnt vmcnt(5)
	v_fmamk_f32 v184, v169, 0x3a000000, v177
	v_rcp_f32_e32 v184, v184
	v_and_b32_e32 v129, 0xffff0000, v228
	v_lshlrev_b32_e32 v128, 16, v228
	v_and_b32_e32 v131, 0xffff0000, v229
	v_lshlrev_b32_e32 v130, 16, v229
	v_and_b32_e32 v133, 0xffff0000, v230
	v_lshlrev_b32_e32 v132, 16, v230
	v_and_b32_e32 v135, 0xffff0000, v231
	v_lshlrev_b32_e32 v134, 16, v231
	v_pk_mul_f32 v[128:129], v[148:149], v[128:129]
	v_pk_mul_f32 v[130:131], v[150:151], v[130:131]
	v_pk_mul_f32 v[132:133], v[152:153], v[132:133]
	v_pk_mul_f32 v[134:135], v[154:155], v[134:135]
	v_pk_fma_f32 v[44:45], v[44:45], v[184:185], v[128:129] op_sel_hi:[1,0,1]
	v_pk_fma_f32 v[46:47], v[46:47], v[184:185], v[130:131] op_sel_hi:[1,0,1]
	v_pk_fma_f32 v[40:41], v[40:41], v[184:185], v[132:133] op_sel_hi:[1,0,1]
	v_pk_fma_f32 v[42:43], v[42:43], v[184:185], v[134:135] op_sel_hi:[1,0,1]
	v_pk_mul_f32 v[182:183], v[44:45], v[44:45]
	v_pk_fma_f32 v[182:183], v[46:47], v[46:47], v[182:183]
	v_pk_fma_f32 v[182:183], v[40:41], v[40:41], v[182:183]
	v_pk_fma_f32 v[182:183], v[42:43], v[42:43], v[182:183]
	s_waitcnt vmcnt(4)
	v_and_b32_e32 v129, 0xffff0000, v232
	v_lshlrev_b32_e32 v128, 16, v232
	v_and_b32_e32 v131, 0xffff0000, v233
	v_lshlrev_b32_e32 v130, 16, v233
	v_and_b32_e32 v133, 0xffff0000, v234
	v_lshlrev_b32_e32 v132, 16, v234
	v_and_b32_e32 v135, 0xffff0000, v235
	v_lshlrev_b32_e32 v134, 16, v235
	v_pk_mul_f32 v[128:129], v[156:157], v[128:129]
	v_pk_mul_f32 v[130:131], v[158:159], v[130:131]
	v_pk_mul_f32 v[132:133], v[160:161], v[132:133]
	v_pk_mul_f32 v[134:135], v[162:163], v[134:135]
	v_pk_fma_f32 v[36:37], v[36:37], v[184:185], v[128:129] op_sel_hi:[1,0,1]
	v_pk_fma_f32 v[38:39], v[38:39], v[184:185], v[130:131] op_sel_hi:[1,0,1]
	v_pk_fma_f32 v[32:33], v[32:33], v[184:185], v[132:133] op_sel_hi:[1,0,1]
	v_pk_fma_f32 v[34:35], v[34:35], v[184:185], v[134:135] op_sel_hi:[1,0,1]
	v_pk_fma_f32 v[182:183], v[36:37], v[36:37], v[182:183]
	v_pk_fma_f32 v[182:183], v[38:39], v[38:39], v[182:183]
	v_pk_fma_f32 v[182:183], v[32:33], v[32:33], v[182:183]
	v_pk_fma_f32 v[182:183], v[34:35], v[34:35], v[182:183]
	v_add_f32_e32 v169, v182, v183
	s_waitcnt vmcnt(3)
	v_fmamk_f32 v184, v170, 0x3a000000, v177
	v_rcp_f32_e32 v184, v184
	v_and_b32_e32 v129, 0xffff0000, v236
	v_lshlrev_b32_e32 v128, 16, v236
	v_and_b32_e32 v131, 0xffff0000, v237
	v_lshlrev_b32_e32 v130, 16, v237
	v_and_b32_e32 v133, 0xffff0000, v238
	v_lshlrev_b32_e32 v132, 16, v238
	v_and_b32_e32 v135, 0xffff0000, v239
	v_lshlrev_b32_e32 v134, 16, v239
	v_pk_mul_f32 v[128:129], v[148:149], v[128:129]
	v_pk_mul_f32 v[130:131], v[150:151], v[130:131]
	v_pk_mul_f32 v[132:133], v[152:153], v[132:133]
	v_pk_mul_f32 v[134:135], v[154:155], v[134:135]
	v_pk_fma_f32 v[28:29], v[28:29], v[184:185], v[128:129] op_sel_hi:[1,0,1]
	v_pk_fma_f32 v[30:31], v[30:31], v[184:185], v[130:131] op_sel_hi:[1,0,1]
	v_pk_fma_f32 v[24:25], v[24:25], v[184:185], v[132:133] op_sel_hi:[1,0,1]
	v_pk_fma_f32 v[26:27], v[26:27], v[184:185], v[134:135] op_sel_hi:[1,0,1]
	v_pk_mul_f32 v[182:183], v[28:29], v[28:29]
	v_pk_fma_f32 v[182:183], v[30:31], v[30:31], v[182:183]
	v_pk_fma_f32 v[182:183], v[24:25], v[24:25], v[182:183]
	v_pk_fma_f32 v[182:183], v[26:27], v[26:27], v[182:183]
	s_waitcnt vmcnt(2)
	v_and_b32_e32 v129, 0xffff0000, v240
	v_lshlrev_b32_e32 v128, 16, v240
	v_and_b32_e32 v131, 0xffff0000, v241
	v_lshlrev_b32_e32 v130, 16, v241
	v_and_b32_e32 v133, 0xffff0000, v242
	v_lshlrev_b32_e32 v132, 16, v242
	v_and_b32_e32 v135, 0xffff0000, v243
	v_lshlrev_b32_e32 v134, 16, v243
	v_pk_mul_f32 v[128:129], v[156:157], v[128:129]
	v_pk_mul_f32 v[130:131], v[158:159], v[130:131]
	v_pk_mul_f32 v[132:133], v[160:161], v[132:133]
	v_pk_mul_f32 v[134:135], v[162:163], v[134:135]
	v_pk_fma_f32 v[20:21], v[20:21], v[184:185], v[128:129] op_sel_hi:[1,0,1]
	v_pk_fma_f32 v[22:23], v[22:23], v[184:185], v[130:131] op_sel_hi:[1,0,1]
	v_pk_fma_f32 v[16:17], v[16:17], v[184:185], v[132:133] op_sel_hi:[1,0,1]
	v_pk_fma_f32 v[18:19], v[18:19], v[184:185], v[134:135] op_sel_hi:[1,0,1]
	v_pk_fma_f32 v[182:183], v[20:21], v[20:21], v[182:183]
	v_pk_fma_f32 v[182:183], v[22:23], v[22:23], v[182:183]
	v_pk_fma_f32 v[182:183], v[16:17], v[16:17], v[182:183]
	v_pk_fma_f32 v[182:183], v[18:19], v[18:19], v[182:183]
	v_add_f32_e32 v170, v182, v183
	s_waitcnt vmcnt(1)
	v_fmamk_f32 v184, v171, 0x3a000000, v177
	v_rcp_f32_e32 v184, v184
	v_and_b32_e32 v129, 0xffff0000, v244
	v_lshlrev_b32_e32 v128, 16, v244
	v_and_b32_e32 v131, 0xffff0000, v245
	v_lshlrev_b32_e32 v130, 16, v245
	v_and_b32_e32 v133, 0xffff0000, v246
	v_lshlrev_b32_e32 v132, 16, v246
	v_and_b32_e32 v135, 0xffff0000, v247
	v_lshlrev_b32_e32 v134, 16, v247
	v_pk_mul_f32 v[128:129], v[148:149], v[128:129]
	v_pk_mul_f32 v[130:131], v[150:151], v[130:131]
	v_pk_mul_f32 v[132:133], v[152:153], v[132:133]
	v_pk_mul_f32 v[134:135], v[154:155], v[134:135]
	v_pk_fma_f32 v[12:13], v[12:13], v[184:185], v[128:129] op_sel_hi:[1,0,1]
	v_pk_fma_f32 v[14:15], v[14:15], v[184:185], v[130:131] op_sel_hi:[1,0,1]
	v_pk_fma_f32 v[8:9], v[8:9], v[184:185], v[132:133] op_sel_hi:[1,0,1]
	v_pk_fma_f32 v[10:11], v[10:11], v[184:185], v[134:135] op_sel_hi:[1,0,1]
	v_pk_mul_f32 v[182:183], v[12:13], v[12:13]
	v_pk_fma_f32 v[182:183], v[14:15], v[14:15], v[182:183]
	v_pk_fma_f32 v[182:183], v[8:9], v[8:9], v[182:183]
	v_pk_fma_f32 v[182:183], v[10:11], v[10:11], v[182:183]
	s_waitcnt vmcnt(0)
	v_and_b32_e32 v129, 0xffff0000, v248
	v_lshlrev_b32_e32 v128, 16, v248
	v_and_b32_e32 v131, 0xffff0000, v249
	v_lshlrev_b32_e32 v130, 16, v249
	v_and_b32_e32 v133, 0xffff0000, v250
	v_lshlrev_b32_e32 v132, 16, v250
	v_and_b32_e32 v135, 0xffff0000, v251
	v_lshlrev_b32_e32 v134, 16, v251
	v_pk_mul_f32 v[128:129], v[156:157], v[128:129]
	v_pk_mul_f32 v[130:131], v[158:159], v[130:131]
	v_pk_mul_f32 v[132:133], v[160:161], v[132:133]
	v_pk_mul_f32 v[134:135], v[162:163], v[134:135]
	v_pk_fma_f32 v[4:5], v[4:5], v[184:185], v[128:129] op_sel_hi:[1,0,1]
	v_pk_fma_f32 v[6:7], v[6:7], v[184:185], v[130:131] op_sel_hi:[1,0,1]
	v_pk_fma_f32 v[0:1], v[0:1], v[184:185], v[132:133] op_sel_hi:[1,0,1]
	v_pk_fma_f32 v[2:3], v[2:3], v[184:185], v[134:135] op_sel_hi:[1,0,1]
	v_pk_fma_f32 v[182:183], v[4:5], v[4:5], v[182:183]
	v_pk_fma_f32 v[182:183], v[6:7], v[6:7], v[182:183]
	v_pk_fma_f32 v[182:183], v[0:1], v[0:1], v[182:183]
	v_pk_fma_f32 v[182:183], v[2:3], v[2:3], v[182:183]
	v_add_f32_e32 v171, v182, v183
	global_load_dwordx4 v[148:151], v252, s[86:87] offset:0
	global_load_dwordx4 v[152:155], v252, s[86:87] offset:16
	global_load_dwordx4 v[156:159], v252, s[86:87] offset:512
	global_load_dwordx4 v[160:163], v252, s[86:87] offset:528
	v_xor_b32_e32 v128, 16, v186
	v_xor_b32_e32 v129, 32, v186
	v_lshlrev_b32_e32 v128, 2, v128
	v_lshlrev_b32_e32 v129, 2, v129
	ds_bpermute_b32 v188, v128, v164
	ds_bpermute_b32 v189, v128, v165
	ds_bpermute_b32 v190, v128, v166
	ds_bpermute_b32 v191, v128, v167
	ds_bpermute_b32 v192, v128, v168
	ds_bpermute_b32 v193, v128, v169
	ds_bpermute_b32 v194, v128, v170
	ds_bpermute_b32 v195, v128, v171
	s_waitcnt lgkmcnt(7)
	v_add_f32_e32 v164, v164, v188
	s_waitcnt lgkmcnt(6)
	v_add_f32_e32 v165, v165, v189
	s_waitcnt lgkmcnt(5)
	v_add_f32_e32 v166, v166, v190
	s_waitcnt lgkmcnt(4)
	v_add_f32_e32 v167, v167, v191
	s_waitcnt lgkmcnt(3)
	v_add_f32_e32 v168, v168, v192
	s_waitcnt lgkmcnt(2)
	v_add_f32_e32 v169, v169, v193
	s_waitcnt lgkmcnt(1)
	v_add_f32_e32 v170, v170, v194
	s_waitcnt lgkmcnt(0)
	v_add_f32_e32 v171, v171, v195
	ds_bpermute_b32 v188, v129, v164
	ds_bpermute_b32 v189, v129, v165
	ds_bpermute_b32 v190, v129, v166
	ds_bpermute_b32 v191, v129, v167
	ds_bpermute_b32 v192, v129, v168
	ds_bpermute_b32 v193, v129, v169
	ds_bpermute_b32 v194, v129, v170
	ds_bpermute_b32 v195, v129, v171
	v_cmp_eq_u32_e32 vcc, 0, v173
	s_and_saveexec_b64 s[36:37], vcc
	s_waitcnt lgkmcnt(7)
	v_add_f32_e32 v164, v164, v188
	global_atomic_add_f32 v253, v164, s[16:17]
	s_waitcnt lgkmcnt(6)
	v_add_f32_e32 v165, v165, v189
	global_atomic_add_f32 v253, v165, s[16:17] offset:64
	s_waitcnt lgkmcnt(5)
	v_add_f32_e32 v166, v166, v190
	global_atomic_add_f32 v253, v166, s[16:17] offset:128
	s_waitcnt lgkmcnt(4)
	v_add_f32_e32 v167, v167, v191
	global_atomic_add_f32 v253, v167, s[16:17] offset:192
	s_waitcnt lgkmcnt(3)
	v_add_f32_e32 v168, v168, v192
	global_atomic_add_f32 v253, v168, s[16:17] offset:512
	s_waitcnt lgkmcnt(2)
	v_add_f32_e32 v169, v169, v193
	global_atomic_add_f32 v253, v169, s[16:17] offset:576
	s_waitcnt lgkmcnt(1)
	v_add_f32_e32 v170, v170, v194
	global_atomic_add_f32 v253, v170, s[16:17] offset:640
	s_waitcnt lgkmcnt(0)
	v_add_f32_e32 v171, v171, v195
	global_atomic_add_f32 v253, v171, s[16:17] offset:704
	s_or_b64 exec, exec, s[36:37]
	s_lshl_b32 s2, s2, 6
	s_ashr_i32 s3, s2, 31
	s_lshl_b64 s[2:3], s[2:3], 2
	s_waitcnt vmcnt(0)
	s_add_u32 s24, s42, s2
	s_addc_u32 s25, s43, s3
	v_cmp_eq_u32_e32 vcc, 0, v173
	v_cmp_eq_u32_e64 s[2:3], 0, v172
	s_and_b64 s[30:31], s[2:3], vcc
	v_mov_b32_e32 v181, 1
	s_and_saveexec_b64 s[2:3], s[30:31]
	global_atomic_add v139, v181, s[24:25]
	s_or_b64 exec, exec, s[2:3]
	s_mov_b32 s29, 0x100001
	s_branch .Lp6_spin

.Lp6_part2:
	global_load_dword v164, v253, s[16:17] sc1
	global_load_dword v165, v253, s[16:17] offset:64 sc1
	global_load_dword v166, v253, s[16:17] offset:128 sc1
	global_load_dword v167, v253, s[16:17] offset:192 sc1
	global_load_dword v168, v253, s[16:17] offset:512 sc1
	global_load_dword v169, v253, s[16:17] offset:576 sc1
	global_load_dword v170, v253, s[16:17] offset:640 sc1
	global_load_dword v171, v253, s[16:17] offset:704 sc1
	s_waitcnt vmcnt(7)
	v_fmamk_f32 v128, v164, 0x3a000000, v177
	v_mul_f32_e32 v129, 0x4f800000, v128
	v_cmp_gt_f32_e32 vcc, s9, v128
	s_nop 1
	v_cndmask_b32_e32 v128, v128, v129, vcc
	v_sqrt_f32_e32 v129, v128
	s_nop 0
	v_add_u32_e32 v130, -1, v129
	v_add_u32_e32 v131, 1, v129
	v_fma_f32 v132, -v130, v129, v128
	v_fma_f32 v133, -v131, v129, v128
	v_cmp_ge_f32_e64 s[2:3], 0, v132
	s_nop 1
	v_cndmask_b32_e64 v129, v129, v130, s[2:3]
	v_cmp_lt_f32_e64 s[2:3], 0, v133
	s_nop 1
	v_cndmask_b32_e64 v129, v129, v131, s[2:3]
	v_mul_f32_e32 v130, 0x37800000, v129
	v_cndmask_b32_e32 v129, v129, v130, vcc
	v_cmp_class_f32_e32 vcc, v128, v178
	s_nop 1
	v_cndmask_b32_e32 v128, v129, v128, vcc
	v_div_scale_f32 v129, s[2:3], v128, v128, 1.0
	v_rcp_f32_e32 v130, v129
	v_div_scale_f32 v131, vcc, 1.0, v128, 1.0
	v_fma_f32 v132, -v129, v130, 1.0
	v_fmac_f32_e32 v130, v132, v130
	v_mul_f32_e32 v132, v131, v130
	v_fma_f32 v133, -v129, v132, v131
	v_fmac_f32_e32 v132, v133, v130
	v_fma_f32 v129, -v129, v132, v131
	v_div_fmas_f32 v129, v129, v130, v132
	v_div_fixup_f32 v184, v129, v128, 1.0
	s_mov_b32 s100, s64
	s_mov_b32 s101, s65
	v_pk_mul_f32 v[188:189], v[124:125], v[184:185] op_sel_hi:[1,0]
	v_pk_mul_f32 v[190:191], v[126:127], v[184:185] op_sel_hi:[1,0]
	v_pk_mul_f32 v[192:193], v[120:121], v[184:185] op_sel_hi:[1,0]
	v_pk_mul_f32 v[194:195], v[122:123], v[184:185] op_sel_hi:[1,0]
	v_pk_mul_f32 v[188:189], v[148:149], v[188:189]
	v_pk_mul_f32 v[190:191], v[150:151], v[190:191]
	v_pk_mul_f32 v[192:193], v[152:153], v[192:193]
	v_pk_mul_f32 v[194:195], v[154:155], v[194:195]
	s_nop 0
	global_store_dwordx4 v185, v[188:191], s[100:101] offset:0
	global_store_dwordx4 v185, v[192:195], s[100:101] offset:16
	v_pk_mul_f32 v[196:197], v[116:117], v[184:185] op_sel_hi:[1,0]
	v_pk_mul_f32 v[198:199], v[118:119], v[184:185] op_sel_hi:[1,0]
	v_pk_mul_f32 v[200:201], v[112:113], v[184:185] op_sel_hi:[1,0]
	v_pk_mul_f32 v[202:203], v[114:115], v[184:185] op_sel_hi:[1,0]
	v_pk_mul_f32 v[196:197], v[156:157], v[196:197]
	v_pk_mul_f32 v[198:199], v[158:159], v[198:199]
	v_pk_mul_f32 v[200:201], v[160:161], v[200:201]
	v_pk_mul_f32 v[202:203], v[162:163], v[202:203]
	s_nop 0
	global_store_dwordx4 v185, v[196:199], s[100:101] offset:512
	global_store_dwordx4 v185, v[200:203], s[100:101] offset:528
	s_waitcnt vmcnt(10)
	v_fmamk_f32 v128, v165, 0x3a000000, v177
	v_mul_f32_e32 v129, 0x4f800000, v128
	v_cmp_gt_f32_e32 vcc, s9, v128
	s_nop 1
	v_cndmask_b32_e32 v128, v128, v129, vcc
	v_sqrt_f32_e32 v129, v128
	s_nop 0
	v_add_u32_e32 v130, -1, v129
	v_add_u32_e32 v131, 1, v129
	v_fma_f32 v132, -v130, v129, v128
	v_fma_f32 v133, -v131, v129, v128
	v_cmp_ge_f32_e64 s[2:3], 0, v132
	s_nop 1
	v_cndmask_b32_e64 v129, v129, v130, s[2:3]
	v_cmp_lt_f32_e64 s[2:3], 0, v133
	s_nop 1
	v_cndmask_b32_e64 v129, v129, v131, s[2:3]
	v_mul_f32_e32 v130, 0x37800000, v129
	v_cndmask_b32_e32 v129, v129, v130, vcc
	v_cmp_class_f32_e32 vcc, v128, v178
	s_nop 1
	v_cndmask_b32_e32 v128, v129, v128, vcc
	v_div_scale_f32 v129, s[2:3], v128, v128, 1.0
	v_rcp_f32_e32 v130, v129
	v_div_scale_f32 v131, vcc, 1.0, v128, 1.0
	v_fma_f32 v132, -v129, v130, 1.0
	v_fmac_f32_e32 v130, v132, v130
	v_mul_f32_e32 v132, v131, v130
	v_fma_f32 v133, -v129, v132, v131
	v_fmac_f32_e32 v132, v133, v130
	v_fma_f32 v129, -v129, v132, v131
	v_div_fmas_f32 v129, v129, v130, v132
	v_div_fixup_f32 v184, v129, v128, 1.0
	s_add_u32 s100, s64, 0x20000
	s_addc_u32 s101, s65, 0
	v_pk_mul_f32 v[204:205], v[108:109], v[184:185] op_sel_hi:[1,0]
	v_pk_mul_f32 v[206:207], v[110:111], v[184:185] op_sel_hi:[1,0]
	v_pk_mul_f32 v[208:209], v[104:105], v[184:185] op_sel_hi:[1,0]
	v_pk_mul_f32 v[210:211], v[106:107], v[184:185] op_sel_hi:[1,0]
	v_pk_mul_f32 v[204:205], v[148:149], v[204:205]
	v_pk_mul_f32 v[206:207], v[150:151], v[206:207]
	v_pk_mul_f32 v[208:209], v[152:153], v[208:209]
	v_pk_mul_f32 v[210:211], v[154:155], v[210:211]
	s_nop 0
	global_store_dwordx4 v185, v[204:207], s[100:101] offset:0
	global_store_dwordx4 v185, v[208:211], s[100:101] offset:16
	v_pk_mul_f32 v[212:213], v[100:101], v[184:185] op_sel_hi:[1,0]
	v_pk_mul_f32 v[214:215], v[102:103], v[184:185] op_sel_hi:[1,0]
	v_pk_mul_f32 v[216:217], v[96:97], v[184:185] op_sel_hi:[1,0]
	v_pk_mul_f32 v[218:219], v[98:99], v[184:185] op_sel_hi:[1,0]
	v_pk_mul_f32 v[212:213], v[156:157], v[212:213]
	v_pk_mul_f32 v[214:215], v[158:159], v[214:215]
	v_pk_mul_f32 v[216:217], v[160:161], v[216:217]
	v_pk_mul_f32 v[218:219], v[162:163], v[218:219]
	s_nop 0
	global_store_dwordx4 v185, v[212:215], s[100:101] offset:512
	global_store_dwordx4 v185, v[216:219], s[100:101] offset:528
	s_waitcnt vmcnt(13)
	v_fmamk_f32 v128, v166, 0x3a000000, v177
	v_mul_f32_e32 v129, 0x4f800000, v128
	v_cmp_gt_f32_e32 vcc, s9, v128
	s_nop 1
	v_cndmask_b32_e32 v128, v128, v129, vcc
	v_sqrt_f32_e32 v129, v128
	s_nop 0
	v_add_u32_e32 v130, -1, v129
	v_add_u32_e32 v131, 1, v129
	v_fma_f32 v132, -v130, v129, v128
	v_fma_f32 v133, -v131, v129, v128
	v_cmp_ge_f32_e64 s[2:3], 0, v132
	s_nop 1
	v_cndmask_b32_e64 v129, v129, v130, s[2:3]
	v_cmp_lt_f32_e64 s[2:3], 0, v133
	s_nop 1
	v_cndmask_b32_e64 v129, v129, v131, s[2:3]
	v_mul_f32_e32 v130, 0x37800000, v129
	v_cndmask_b32_e32 v129, v129, v130, vcc
	v_cmp_class_f32_e32 vcc, v128, v178
	s_nop 1
	v_cndmask_b32_e32 v128, v129, v128, vcc
	v_div_scale_f32 v129, s[2:3], v128, v128, 1.0
	v_rcp_f32_e32 v130, v129
	v_div_scale_f32 v131, vcc, 1.0, v128, 1.0
	v_fma_f32 v132, -v129, v130, 1.0
	v_fmac_f32_e32 v130, v132, v130
	v_mul_f32_e32 v132, v131, v130
	v_fma_f32 v133, -v129, v132, v131
	v_fmac_f32_e32 v132, v133, v130
	v_fma_f32 v129, -v129, v132, v131
	v_div_fmas_f32 v129, v129, v130, v132
	v_div_fixup_f32 v184, v129, v128, 1.0
	s_add_u32 s100, s64, 0x40000
	s_addc_u32 s101, s65, 0
	v_pk_mul_f32 v[220:221], v[92:93], v[184:185] op_sel_hi:[1,0]
	v_pk_mul_f32 v[222:223], v[94:95], v[184:185] op_sel_hi:[1,0]
	v_pk_mul_f32 v[224:225], v[88:89], v[184:185] op_sel_hi:[1,0]
	v_pk_mul_f32 v[226:227], v[90:91], v[184:185] op_sel_hi:[1,0]
	v_pk_mul_f32 v[220:221], v[148:149], v[220:221]
	v_pk_mul_f32 v[222:223], v[150:151], v[222:223]
	v_pk_mul_f32 v[224:225], v[152:153], v[224:225]
	v_pk_mul_f32 v[226:227], v[154:155], v[226:227]
	s_nop 0
	global_store_dwordx4 v185, v[220:223], s[100:101] offset:0
	global_store_dwordx4 v185, v[224:227], s[100:101] offset:16
	v_pk_mul_f32 v[228:229], v[84:85], v[184:185] op_sel_hi:[1,0]
	v_pk_mul_f32 v[230:231], v[86:87], v[184:185] op_sel_hi:[1,0]
	v_pk_mul_f32 v[232:233], v[80:81], v[184:185] op_sel_hi:[1,0]
	v_pk_mul_f32 v[234:235], v[82:83], v[184:185] op_sel_hi:[1,0]
	v_pk_mul_f32 v[228:229], v[156:157], v[228:229]
	v_pk_mul_f32 v[230:231], v[158:159], v[230:231]
	v_pk_mul_f32 v[232:233], v[160:161], v[232:233]
	v_pk_mul_f32 v[234:235], v[162:163], v[234:235]
	s_nop 0
	global_store_dwordx4 v185, v[228:231], s[100:101] offset:512
	global_store_dwordx4 v185, v[232:235], s[100:101] offset:528
	s_waitcnt vmcnt(16)
	v_fmamk_f32 v128, v167, 0x3a000000, v177
	v_mul_f32_e32 v129, 0x4f800000, v128
	v_cmp_gt_f32_e32 vcc, s9, v128
	s_nop 1
	v_cndmask_b32_e32 v128, v128, v129, vcc
	v_sqrt_f32_e32 v129, v128
	s_nop 0
	v_add_u32_e32 v130, -1, v129
	v_add_u32_e32 v131, 1, v129
	v_fma_f32 v132, -v130, v129, v128
	v_fma_f32 v133, -v131, v129, v128
	v_cmp_ge_f32_e64 s[2:3], 0, v132
	s_nop 1
	v_cndmask_b32_e64 v129, v129, v130, s[2:3]
	v_cmp_lt_f32_e64 s[2:3], 0, v133
	s_nop 1
	v_cndmask_b32_e64 v129, v129, v131, s[2:3]
	v_mul_f32_e32 v130, 0x37800000, v129
	v_cndmask_b32_e32 v129, v129, v130, vcc
	v_cmp_class_f32_e32 vcc, v128, v178
	s_nop 1
	v_cndmask_b32_e32 v128, v129, v128, vcc
	v_div_scale_f32 v129, s[2:3], v128, v128, 1.0
	v_rcp_f32_e32 v130, v129
	v_div_scale_f32 v131, vcc, 1.0, v128, 1.0
	v_fma_f32 v132, -v129, v130, 1.0
	v_fmac_f32_e32 v130, v132, v130
	v_mul_f32_e32 v132, v131, v130
	v_fma_f32 v133, -v129, v132, v131
	v_fmac_f32_e32 v132, v133, v130
	v_fma_f32 v129, -v129, v132, v131
	v_div_fmas_f32 v129, v129, v130, v132
	v_div_fixup_f32 v184, v129, v128, 1.0
	s_add_u32 s100, s64, 0x60000
	s_addc_u32 s101, s65, 0
	v_pk_mul_f32 v[236:237], v[76:77], v[184:185] op_sel_hi:[1,0]
	v_pk_mul_f32 v[238:239], v[78:79], v[184:185] op_sel_hi:[1,0]
	v_pk_mul_f32 v[240:241], v[72:73], v[184:185] op_sel_hi:[1,0]
	v_pk_mul_f32 v[242:243], v[74:75], v[184:185] op_sel_hi:[1,0]
	v_pk_mul_f32 v[236:237], v[148:149], v[236:237]
	v_pk_mul_f32 v[238:239], v[150:151], v[238:239]
	v_pk_mul_f32 v[240:241], v[152:153], v[240:241]
	v_pk_mul_f32 v[242:243], v[154:155], v[242:243]
	s_nop 0
	global_store_dwordx4 v185, v[236:239], s[100:101] offset:0
	global_store_dwordx4 v185, v[240:243], s[100:101] offset:16
	v_pk_mul_f32 v[244:245], v[68:69], v[184:185] op_sel_hi:[1,0]
	v_pk_mul_f32 v[246:247], v[70:71], v[184:185] op_sel_hi:[1,0]
	v_pk_mul_f32 v[248:249], v[64:65], v[184:185] op_sel_hi:[1,0]
	v_pk_mul_f32 v[250:251], v[66:67], v[184:185] op_sel_hi:[1,0]
	v_pk_mul_f32 v[244:245], v[156:157], v[244:245]
	v_pk_mul_f32 v[246:247], v[158:159], v[246:247]
	v_pk_mul_f32 v[248:249], v[160:161], v[248:249]
	v_pk_mul_f32 v[250:251], v[162:163], v[250:251]
	s_nop 0
	global_store_dwordx4 v185, v[244:247], s[100:101] offset:512
	global_store_dwordx4 v185, v[248:251], s[100:101] offset:528
	s_waitcnt vmcnt(19)
	v_fmamk_f32 v128, v168, 0x3a000000, v177
	v_mul_f32_e32 v129, 0x4f800000, v128
	v_cmp_gt_f32_e32 vcc, s9, v128
	s_nop 1
	v_cndmask_b32_e32 v128, v128, v129, vcc
	v_sqrt_f32_e32 v129, v128
	s_nop 0
	v_add_u32_e32 v130, -1, v129
	v_add_u32_e32 v131, 1, v129
	v_fma_f32 v132, -v130, v129, v128
	v_fma_f32 v133, -v131, v129, v128
	v_cmp_ge_f32_e64 s[2:3], 0, v132
	s_nop 1
	v_cndmask_b32_e64 v129, v129, v130, s[2:3]
	v_cmp_lt_f32_e64 s[2:3], 0, v133
	s_nop 1
	v_cndmask_b32_e64 v129, v129, v131, s[2:3]
	v_mul_f32_e32 v130, 0x37800000, v129
	v_cndmask_b32_e32 v129, v129, v130, vcc
	v_cmp_class_f32_e32 vcc, v128, v178
	s_nop 1
	v_cndmask_b32_e32 v128, v129, v128, vcc
	v_div_scale_f32 v129, s[2:3], v128, v128, 1.0
	v_rcp_f32_e32 v130, v129
	v_div_scale_f32 v131, vcc, 1.0, v128, 1.0
	v_fma_f32 v132, -v129, v130, 1.0
	v_fmac_f32_e32 v130, v132, v130
	v_mul_f32_e32 v132, v131, v130
	v_fma_f32 v133, -v129, v132, v131
	v_fmac_f32_e32 v132, v133, v130
	v_fma_f32 v129, -v129, v132, v131
	v_div_fmas_f32 v129, v129, v130, v132
	v_div_fixup_f32 v184, v129, v128, 1.0
	s_add_u32 s100, s64, 0x100000
	s_addc_u32 s101, s65, 0
	v_pk_mul_f32 v[188:189], v[60:61], v[184:185] op_sel_hi:[1,0]
	v_pk_mul_f32 v[190:191], v[62:63], v[184:185] op_sel_hi:[1,0]
	v_pk_mul_f32 v[192:193], v[56:57], v[184:185] op_sel_hi:[1,0]
	v_pk_mul_f32 v[194:195], v[58:59], v[184:185] op_sel_hi:[1,0]
	v_pk_mul_f32 v[188:189], v[148:149], v[188:189]
	v_pk_mul_f32 v[190:191], v[150:151], v[190:191]
	v_pk_mul_f32 v[192:193], v[152:153], v[192:193]
	v_pk_mul_f32 v[194:195], v[154:155], v[194:195]
	s_nop 0
	global_store_dwordx4 v185, v[188:191], s[100:101] offset:0
	global_store_dwordx4 v185, v[192:195], s[100:101] offset:16
	v_pk_mul_f32 v[196:197], v[52:53], v[184:185] op_sel_hi:[1,0]
	v_pk_mul_f32 v[198:199], v[54:55], v[184:185] op_sel_hi:[1,0]
	v_pk_mul_f32 v[200:201], v[48:49], v[184:185] op_sel_hi:[1,0]
	v_pk_mul_f32 v[202:203], v[50:51], v[184:185] op_sel_hi:[1,0]
	v_pk_mul_f32 v[196:197], v[156:157], v[196:197]
	v_pk_mul_f32 v[198:199], v[158:159], v[198:199]
	v_pk_mul_f32 v[200:201], v[160:161], v[200:201]
	v_pk_mul_f32 v[202:203], v[162:163], v[202:203]
	s_nop 0
	global_store_dwordx4 v185, v[196:199], s[100:101] offset:512
	global_store_dwordx4 v185, v[200:203], s[100:101] offset:528
	s_waitcnt vmcnt(22)
	v_fmamk_f32 v128, v169, 0x3a000000, v177
	v_mul_f32_e32 v129, 0x4f800000, v128
	v_cmp_gt_f32_e32 vcc, s9, v128
	s_nop 1
	v_cndmask_b32_e32 v128, v128, v129, vcc
	v_sqrt_f32_e32 v129, v128
	s_nop 0
	v_add_u32_e32 v130, -1, v129
	v_add_u32_e32 v131, 1, v129
	v_fma_f32 v132, -v130, v129, v128
	v_fma_f32 v133, -v131, v129, v128
	v_cmp_ge_f32_e64 s[2:3], 0, v132
	s_nop 1
	v_cndmask_b32_e64 v129, v129, v130, s[2:3]
	v_cmp_lt_f32_e64 s[2:3], 0, v133
	s_nop 1
	v_cndmask_b32_e64 v129, v129, v131, s[2:3]
	v_mul_f32_e32 v130, 0x37800000, v129
	v_cndmask_b32_e32 v129, v129, v130, vcc
	v_cmp_class_f32_e32 vcc, v128, v178
	s_nop 1
	v_cndmask_b32_e32 v128, v129, v128, vcc
	v_div_scale_f32 v129, s[2:3], v128, v128, 1.0
	v_rcp_f32_e32 v130, v129
	v_div_scale_f32 v131, vcc, 1.0, v128, 1.0
	v_fma_f32 v132, -v129, v130, 1.0
	v_fmac_f32_e32 v130, v132, v130
	v_mul_f32_e32 v132, v131, v130
	v_fma_f32 v133, -v129, v132, v131
	v_fmac_f32_e32 v132, v133, v130
	v_fma_f32 v129, -v129, v132, v131
	v_div_fmas_f32 v129, v129, v130, v132
	v_div_fixup_f32 v184, v129, v128, 1.0
	s_add_u32 s100, s64, 0x120000
	s_addc_u32 s101, s65, 0
	v_pk_mul_f32 v[204:205], v[44:45], v[184:185] op_sel_hi:[1,0]
	v_pk_mul_f32 v[206:207], v[46:47], v[184:185] op_sel_hi:[1,0]
	v_pk_mul_f32 v[208:209], v[40:41], v[184:185] op_sel_hi:[1,0]
	v_pk_mul_f32 v[210:211], v[42:43], v[184:185] op_sel_hi:[1,0]
	v_pk_mul_f32 v[204:205], v[148:149], v[204:205]
	v_pk_mul_f32 v[206:207], v[150:151], v[206:207]
	v_pk_mul_f32 v[208:209], v[152:153], v[208:209]
	v_pk_mul_f32 v[210:211], v[154:155], v[210:211]
	s_nop 0
	global_store_dwordx4 v185, v[204:207], s[100:101] offset:0
	global_store_dwordx4 v185, v[208:211], s[100:101] offset:16
	v_pk_mul_f32 v[212:213], v[36:37], v[184:185] op_sel_hi:[1,0]
	v_pk_mul_f32 v[214:215], v[38:39], v[184:185] op_sel_hi:[1,0]
	v_pk_mul_f32 v[216:217], v[32:33], v[184:185] op_sel_hi:[1,0]
	v_pk_mul_f32 v[218:219], v[34:35], v[184:185] op_sel_hi:[1,0]
	v_pk_mul_f32 v[212:213], v[156:157], v[212:213]
	v_pk_mul_f32 v[214:215], v[158:159], v[214:215]
	v_pk_mul_f32 v[216:217], v[160:161], v[216:217]
	v_pk_mul_f32 v[218:219], v[162:163], v[218:219]
	s_nop 0
	global_store_dwordx4 v185, v[212:215], s[100:101] offset:512
	global_store_dwordx4 v185, v[216:219], s[100:101] offset:528
	s_waitcnt vmcnt(25)
	v_fmamk_f32 v128, v170, 0x3a000000, v177
	v_mul_f32_e32 v129, 0x4f800000, v128
	v_cmp_gt_f32_e32 vcc, s9, v128
	s_nop 1
	v_cndmask_b32_e32 v128, v128, v129, vcc
	v_sqrt_f32_e32 v129, v128
	s_nop 0
	v_add_u32_e32 v130, -1, v129
	v_add_u32_e32 v131, 1, v129
	v_fma_f32 v132, -v130, v129, v128
	v_fma_f32 v133, -v131, v129, v128
	v_cmp_ge_f32_e64 s[2:3], 0, v132
	s_nop 1
	v_cndmask_b32_e64 v129, v129, v130, s[2:3]
	v_cmp_lt_f32_e64 s[2:3], 0, v133
	s_nop 1
	v_cndmask_b32_e64 v129, v129, v131, s[2:3]
	v_mul_f32_e32 v130, 0x37800000, v129
	v_cndmask_b32_e32 v129, v129, v130, vcc
	v_cmp_class_f32_e32 vcc, v128, v178
	s_nop 1
	v_cndmask_b32_e32 v128, v129, v128, vcc
	v_div_scale_f32 v129, s[2:3], v128, v128, 1.0
	v_rcp_f32_e32 v130, v129
	v_div_scale_f32 v131, vcc, 1.0, v128, 1.0
	v_fma_f32 v132, -v129, v130, 1.0
	v_fmac_f32_e32 v130, v132, v130
	v_mul_f32_e32 v132, v131, v130
	v_fma_f32 v133, -v129, v132, v131
	v_fmac_f32_e32 v132, v133, v130
	v_fma_f32 v129, -v129, v132, v131
	v_div_fmas_f32 v129, v129, v130, v132
	v_div_fixup_f32 v184, v129, v128, 1.0
	s_add_u32 s100, s64, 0x140000
	s_addc_u32 s101, s65, 0
	v_pk_mul_f32 v[220:221], v[28:29], v[184:185] op_sel_hi:[1,0]
	v_pk_mul_f32 v[222:223], v[30:31], v[184:185] op_sel_hi:[1,0]
	v_pk_mul_f32 v[224:225], v[24:25], v[184:185] op_sel_hi:[1,0]
	v_pk_mul_f32 v[226:227], v[26:27], v[184:185] op_sel_hi:[1,0]
	v_pk_mul_f32 v[220:221], v[148:149], v[220:221]
	v_pk_mul_f32 v[222:223], v[150:151], v[222:223]
	v_pk_mul_f32 v[224:225], v[152:153], v[224:225]
	v_pk_mul_f32 v[226:227], v[154:155], v[226:227]
	s_nop 0
	global_store_dwordx4 v185, v[220:223], s[100:101] offset:0
	global_store_dwordx4 v185, v[224:227], s[100:101] offset:16
	v_pk_mul_f32 v[228:229], v[20:21], v[184:185] op_sel_hi:[1,0]
	v_pk_mul_f32 v[230:231], v[22:23], v[184:185] op_sel_hi:[1,0]
	v_pk_mul_f32 v[232:233], v[16:17], v[184:185] op_sel_hi:[1,0]
	v_pk_mul_f32 v[234:235], v[18:19], v[184:185] op_sel_hi:[1,0]
	v_pk_mul_f32 v[228:229], v[156:157], v[228:229]
	v_pk_mul_f32 v[230:231], v[158:159], v[230:231]
	v_pk_mul_f32 v[232:233], v[160:161], v[232:233]
	v_pk_mul_f32 v[234:235], v[162:163], v[234:235]
	s_nop 0
	global_store_dwordx4 v185, v[228:231], s[100:101] offset:512
	global_store_dwordx4 v185, v[232:235], s[100:101] offset:528
	s_waitcnt vmcnt(28)
	v_fmamk_f32 v128, v171, 0x3a000000, v177
	v_mul_f32_e32 v129, 0x4f800000, v128
	v_cmp_gt_f32_e32 vcc, s9, v128
	s_nop 1
	v_cndmask_b32_e32 v128, v128, v129, vcc
	v_sqrt_f32_e32 v129, v128
	s_nop 0
	v_add_u32_e32 v130, -1, v129
	v_add_u32_e32 v131, 1, v129
	v_fma_f32 v132, -v130, v129, v128
	v_fma_f32 v133, -v131, v129, v128
	v_cmp_ge_f32_e64 s[2:3], 0, v132
	s_nop 1
	v_cndmask_b32_e64 v129, v129, v130, s[2:3]
	v_cmp_lt_f32_e64 s[2:3], 0, v133
	s_nop 1
	v_cndmask_b32_e64 v129, v129, v131, s[2:3]
	v_mul_f32_e32 v130, 0x37800000, v129
	v_cndmask_b32_e32 v129, v129, v130, vcc
	v_cmp_class_f32_e32 vcc, v128, v178
	s_nop 1
	v_cndmask_b32_e32 v128, v129, v128, vcc
	v_div_scale_f32 v129, s[2:3], v128, v128, 1.0
	v_rcp_f32_e32 v130, v129
	v_div_scale_f32 v131, vcc, 1.0, v128, 1.0
	v_fma_f32 v132, -v129, v130, 1.0
	v_fmac_f32_e32 v130, v132, v130
	v_mul_f32_e32 v132, v131, v130
	v_fma_f32 v133, -v129, v132, v131
	v_fmac_f32_e32 v132, v133, v130
	v_fma_f32 v129, -v129, v132, v131
	v_div_fmas_f32 v129, v129, v130, v132
	v_div_fixup_f32 v184, v129, v128, 1.0
	s_add_u32 s100, s64, 0x160000
	s_addc_u32 s101, s65, 0
	v_pk_mul_f32 v[236:237], v[12:13], v[184:185] op_sel_hi:[1,0]
	v_pk_mul_f32 v[238:239], v[14:15], v[184:185] op_sel_hi:[1,0]
	v_pk_mul_f32 v[240:241], v[8:9], v[184:185] op_sel_hi:[1,0]
	v_pk_mul_f32 v[242:243], v[10:11], v[184:185] op_sel_hi:[1,0]
	v_pk_mul_f32 v[236:237], v[148:149], v[236:237]
	v_pk_mul_f32 v[238:239], v[150:151], v[238:239]
	v_pk_mul_f32 v[240:241], v[152:153], v[240:241]
	v_pk_mul_f32 v[242:243], v[154:155], v[242:243]
	s_nop 0
	global_store_dwordx4 v185, v[236:239], s[100:101] offset:0
	global_store_dwordx4 v185, v[240:243], s[100:101] offset:16
	v_pk_mul_f32 v[244:245], v[4:5], v[184:185] op_sel_hi:[1,0]
	v_pk_mul_f32 v[246:247], v[6:7], v[184:185] op_sel_hi:[1,0]
	v_pk_mul_f32 v[248:249], v[0:1], v[184:185] op_sel_hi:[1,0]
	v_pk_mul_f32 v[250:251], v[2:3], v[184:185] op_sel_hi:[1,0]
	v_pk_mul_f32 v[244:245], v[156:157], v[244:245]
	v_pk_mul_f32 v[246:247], v[158:159], v[246:247]
	v_pk_mul_f32 v[248:249], v[160:161], v[248:249]
	v_pk_mul_f32 v[250:251], v[162:163], v[250:251]
	s_nop 0
	global_store_dwordx4 v185, v[244:247], s[100:101] offset:512
	global_store_dwordx4 v185, v[248:251], s[100:101] offset:528
	s_andn2_b64 vcc, exec, s[22:23]
	s_mov_b64 s[2:3], -1
	s_cbranch_vccnz .LBB0_672
	s_and_b64 vcc, exec, s[0:1]
	s_cbranch_vccnz .LBB0_671
	s_barrier
	s_branch .LBB0_671
